# scan loaders: each next-chunk load issued right after the staging block that frees its registers
# baseline (speedup 1.0000x reference)
.Lyred_first:
	s_cmp_eq_u32 s34, 0x379000
	s_cbranch_scc1 .LBB0_823
	s_andn2_b32 s0, 1, s54
	s_mul_i32 s0, s0, 0xc000
	s_add_i32 s4, s0, 0
	v_add_u32_e32 v28, s4, v103
	v_lshl_add_u64 v[46:47], v[92:93], 0, s[34:35]
	s_and_saveexec_b64 s[0:1], s[10:11]
	s_xor_b64 s[44:45], exec, s[0:1]
	s_cbranch_execz .LBB0_795
	v_lshl_add_u32 v28, v104, 2, v28
	v_add3_u32 v36, v28, v127, s53
	s_waitcnt vmcnt(6)
	s_mov_b32 vcc_lo, 0xaaaaaaaa
	s_mov_b32 vcc_hi, 0xaaaaaaaa
	v_cndmask_b32_e32 v37, v2, v0, vcc
	v_cndmask_b32_e32 v38, v3, v1, vcc
	v_add_u32_e32 v40, -16, v36
	v_cndmask_b32_e32 v36, v36, v40, vcc
	v_mov_b32_dpp v41, v37 quad_perm:[1,0,3,2] row_mask:0xf bank_mask:0xf bound_ctrl:1
	v_mov_b32_dpp v42, v38 quad_perm:[1,0,3,2] row_mask:0xf bank_mask:0xf bound_ctrl:1
	v_cndmask_b32_e32 v37, v0, v41, vcc
	v_cndmask_b32_e32 v38, v1, v42, vcc
	v_cndmask_b32_e32 v41, v41, v2, vcc
	v_cndmask_b32_e32 v42, v42, v3, vcc
	v_lshlrev_b32_e32 v28, 16, v37
	v_and_b32_e32 v29, 0xffff0000, v37
	v_lshlrev_b32_e32 v30, 16, v38
	v_and_b32_e32 v31, 0xffff0000, v38
	ds_write_b128 v36, v[28:31]
	v_lshlrev_b32_e32 v28, 16, v41
	v_and_b32_e32 v29, 0xffff0000, v41
	v_lshlrev_b32_e32 v30, 16, v42
	v_and_b32_e32 v31, 0xffff0000, v42
	ds_write_b128 v36, v[28:31] offset:32

.LBB0_797:
	s_or_b64 exec, exec, s[44:45]
	s_cmpk_gt_u32 s54, 0x7d
	s_cbranch_scc1 .Lld_skip0
	v_add_co_u32_e32 v0, vcc, 0x16bfe000, v46
	s_nop 1
	v_addc_co_u32_e32 v1, vcc, 0, v47, vcc
	global_load_dwordx4 v[0:3], v[0:1], off
.Lld_skip0:
	v_add_u32_e32 v28, s4, v106
	s_and_saveexec_b64 s[0:1], s[12:13]
	s_xor_b64 s[44:45], exec, s[0:1]
	s_cbranch_execz .LBB0_799
	v_lshl_add_u32 v28, v107, 2, v28
	v_add3_u32 v36, v28, v128, s53
	s_waitcnt vmcnt(6)
	s_mov_b32 vcc_lo, 0xaaaaaaaa
	s_mov_b32 vcc_hi, 0xaaaaaaaa
	v_cndmask_b32_e32 v37, v6, v4, vcc
	v_cndmask_b32_e32 v38, v7, v5, vcc
	v_add_u32_e32 v40, -16, v36
	v_cndmask_b32_e32 v36, v36, v40, vcc
	v_mov_b32_dpp v41, v37 quad_perm:[1,0,3,2] row_mask:0xf bank_mask:0xf bound_ctrl:1
	v_mov_b32_dpp v42, v38 quad_perm:[1,0,3,2] row_mask:0xf bank_mask:0xf bound_ctrl:1
	v_cndmask_b32_e32 v37, v4, v41, vcc
	v_cndmask_b32_e32 v38, v5, v42, vcc
	v_cndmask_b32_e32 v41, v41, v6, vcc
	v_cndmask_b32_e32 v42, v42, v7, vcc
	v_lshlrev_b32_e32 v28, 16, v37
	v_and_b32_e32 v29, 0xffff0000, v37
	v_lshlrev_b32_e32 v30, 16, v38
	v_and_b32_e32 v31, 0xffff0000, v38
	ds_write_b128 v36, v[28:31]
	v_lshlrev_b32_e32 v28, 16, v41
	v_and_b32_e32 v29, 0xffff0000, v41
	v_lshlrev_b32_e32 v30, 16, v42
	v_and_b32_e32 v31, 0xffff0000, v42
	ds_write_b128 v36, v[28:31] offset:32
.LBB0_799:
	s_andn2_saveexec_b64 s[44:45], s[44:45]
	s_cbranch_execz .LBB0_801
	v_add_u32_e32 v28, v28, v108
	s_waitcnt vmcnt(6)
	ds_write_b128 v28, v[4:7]
.LBB0_801:
	s_or_b64 exec, exec, s[44:45]
	s_cmpk_gt_u32 s54, 0x7d
	s_cbranch_scc1 .Lld_skip1
	v_add_co_u32_e32 v4, vcc, 0x16bff000, v46
	s_nop 1
	v_addc_co_u32_e32 v5, vcc, 0, v47, vcc
	global_load_dwordx4 v[4:7], v[4:5], off
.Lld_skip1:
	v_add_u32_e32 v28, s4, v109
	s_and_saveexec_b64 s[0:1], s[14:15]
	s_xor_b64 s[44:45], exec, s[0:1]
	s_cbranch_execz .LBB0_803
	v_lshl_add_u32 v28, v110, 2, v28
	v_add3_u32 v36, v28, v129, s53
	s_waitcnt vmcnt(6)
	s_mov_b32 vcc_lo, 0xaaaaaaaa
	s_mov_b32 vcc_hi, 0xaaaaaaaa
	v_cndmask_b32_e32 v37, v10, v8, vcc
	v_cndmask_b32_e32 v38, v11, v9, vcc
	v_add_u32_e32 v40, -16, v36
	v_cndmask_b32_e32 v36, v36, v40, vcc
	v_mov_b32_dpp v41, v37 quad_perm:[1,0,3,2] row_mask:0xf bank_mask:0xf bound_ctrl:1
	v_mov_b32_dpp v42, v38 quad_perm:[1,0,3,2] row_mask:0xf bank_mask:0xf bound_ctrl:1
	v_cndmask_b32_e32 v37, v8, v41, vcc
	v_cndmask_b32_e32 v38, v9, v42, vcc
	v_cndmask_b32_e32 v41, v41, v10, vcc
	v_cndmask_b32_e32 v42, v42, v11, vcc
	v_lshlrev_b32_e32 v28, 16, v37
	v_and_b32_e32 v29, 0xffff0000, v37
	v_lshlrev_b32_e32 v30, 16, v38
	v_and_b32_e32 v31, 0xffff0000, v38
	ds_write_b128 v36, v[28:31]
	v_lshlrev_b32_e32 v28, 16, v41
	v_and_b32_e32 v29, 0xffff0000, v41
	v_lshlrev_b32_e32 v30, 16, v42
	v_and_b32_e32 v31, 0xffff0000, v42
	ds_write_b128 v36, v[28:31] offset:32
.LBB0_803:
	s_andn2_saveexec_b64 s[44:45], s[44:45]
	s_cbranch_execz .LBB0_805
	v_add_u32_e32 v28, v28, v111
	s_waitcnt vmcnt(6)
	ds_write_b128 v28, v[8:11]
.LBB0_805:
	s_or_b64 exec, exec, s[44:45]
	s_cmpk_gt_u32 s54, 0x7d
	s_cbranch_scc1 .Lld_skip2
	v_add_co_u32_e32 v8, vcc, 0x16c00000, v46
	s_nop 1
	v_addc_co_u32_e32 v9, vcc, 0, v47, vcc
	global_load_dwordx4 v[8:11], v[8:9], off
.Lld_skip2:
	v_add_u32_e32 v28, s4, v112
	s_and_saveexec_b64 s[0:1], s[16:17]
	s_xor_b64 s[44:45], exec, s[0:1]
	s_cbranch_execz .LBB0_807
	v_lshl_add_u32 v28, v113, 2, v28
	v_add3_u32 v36, v28, v130, s53
	s_waitcnt vmcnt(6)
	s_mov_b32 vcc_lo, 0xaaaaaaaa
	s_mov_b32 vcc_hi, 0xaaaaaaaa
	v_cndmask_b32_e32 v37, v14, v12, vcc
	v_cndmask_b32_e32 v38, v15, v13, vcc
	v_add_u32_e32 v40, -16, v36
	v_cndmask_b32_e32 v36, v36, v40, vcc
	v_mov_b32_dpp v41, v37 quad_perm:[1,0,3,2] row_mask:0xf bank_mask:0xf bound_ctrl:1
	v_mov_b32_dpp v42, v38 quad_perm:[1,0,3,2] row_mask:0xf bank_mask:0xf bound_ctrl:1
	v_cndmask_b32_e32 v37, v12, v41, vcc
	v_cndmask_b32_e32 v38, v13, v42, vcc
	v_cndmask_b32_e32 v41, v41, v14, vcc
	v_cndmask_b32_e32 v42, v42, v15, vcc
	v_lshlrev_b32_e32 v28, 16, v37
	v_and_b32_e32 v29, 0xffff0000, v37
	v_lshlrev_b32_e32 v30, 16, v38
	v_and_b32_e32 v31, 0xffff0000, v38
	ds_write_b128 v36, v[28:31]
	v_lshlrev_b32_e32 v28, 16, v41
	v_and_b32_e32 v29, 0xffff0000, v41
	v_lshlrev_b32_e32 v30, 16, v42
	v_and_b32_e32 v31, 0xffff0000, v42
	ds_write_b128 v36, v[28:31] offset:32
.LBB0_807:
	s_andn2_saveexec_b64 s[44:45], s[44:45]
	s_cbranch_execz .LBB0_809
	v_add_u32_e32 v28, v28, v114
	s_waitcnt vmcnt(6)
	ds_write_b128 v28, v[12:15]
.LBB0_809:
	s_or_b64 exec, exec, s[44:45]
	s_cmpk_gt_u32 s54, 0x7d
	s_cbranch_scc1 .Lld_skip3
	v_add_co_u32_e32 v12, vcc, 0x16c01000, v46
	s_nop 1
	v_addc_co_u32_e32 v13, vcc, 0, v47, vcc
	global_load_dwordx4 v[12:15], v[12:13], off
.Lld_skip3:
	v_add_u32_e32 v28, s4, v115
	s_and_saveexec_b64 s[0:1], s[18:19]
	s_xor_b64 s[44:45], exec, s[0:1]
	s_cbranch_execz .LBB0_811
	v_lshl_add_u32 v28, v116, 2, v28
	v_add3_u32 v36, v28, v131, s53
	s_waitcnt vmcnt(6)
	s_mov_b32 vcc_lo, 0xaaaaaaaa
	s_mov_b32 vcc_hi, 0xaaaaaaaa
	v_cndmask_b32_e32 v37, v18, v16, vcc
	v_cndmask_b32_e32 v38, v19, v17, vcc
	v_add_u32_e32 v40, -16, v36
	v_cndmask_b32_e32 v36, v36, v40, vcc
	v_mov_b32_dpp v41, v37 quad_perm:[1,0,3,2] row_mask:0xf bank_mask:0xf bound_ctrl:1
	v_mov_b32_dpp v42, v38 quad_perm:[1,0,3,2] row_mask:0xf bank_mask:0xf bound_ctrl:1
	v_cndmask_b32_e32 v37, v16, v41, vcc
	v_cndmask_b32_e32 v38, v17, v42, vcc
	v_cndmask_b32_e32 v41, v41, v18, vcc
	v_cndmask_b32_e32 v42, v42, v19, vcc
	v_lshlrev_b32_e32 v28, 16, v37
	v_and_b32_e32 v29, 0xffff0000, v37
	v_lshlrev_b32_e32 v30, 16, v38
	v_and_b32_e32 v31, 0xffff0000, v38
	ds_write_b128 v36, v[28:31]
	v_lshlrev_b32_e32 v28, 16, v41
	v_and_b32_e32 v29, 0xffff0000, v41
	v_lshlrev_b32_e32 v30, 16, v42
	v_and_b32_e32 v31, 0xffff0000, v42
	ds_write_b128 v36, v[28:31] offset:32
.LBB0_811:
	s_andn2_saveexec_b64 s[44:45], s[44:45]
	s_cbranch_execz .LBB0_813
	v_add_u32_e32 v28, v28, v117
	s_waitcnt vmcnt(6)
	ds_write_b128 v28, v[16:19]
.LBB0_813:
	s_or_b64 exec, exec, s[44:45]
	s_cmpk_gt_u32 s54, 0x7d
	s_cbranch_scc1 .Lld_skip4
	v_add_co_u32_e32 v16, vcc, 0x16c02000, v46
	s_nop 1
	v_addc_co_u32_e32 v17, vcc, 0, v47, vcc
	global_load_dwordx4 v[16:19], v[16:17], off
.Lld_skip4:
	v_add_u32_e32 v28, s4, v118
	s_and_saveexec_b64 s[0:1], s[20:21]
	s_xor_b64 s[44:45], exec, s[0:1]
	s_cbranch_execz .LBB0_815
	v_lshl_add_u32 v28, v119, 2, v28
	v_add3_u32 v36, v28, v132, s53
	s_waitcnt vmcnt(6)
	s_mov_b32 vcc_lo, 0xaaaaaaaa
	s_mov_b32 vcc_hi, 0xaaaaaaaa
	v_cndmask_b32_e32 v37, v22, v20, vcc
	v_cndmask_b32_e32 v38, v23, v21, vcc
	v_add_u32_e32 v40, -16, v36
	v_cndmask_b32_e32 v36, v36, v40, vcc
	v_mov_b32_dpp v41, v37 quad_perm:[1,0,3,2] row_mask:0xf bank_mask:0xf bound_ctrl:1
	v_mov_b32_dpp v42, v38 quad_perm:[1,0,3,2] row_mask:0xf bank_mask:0xf bound_ctrl:1
	v_cndmask_b32_e32 v37, v20, v41, vcc
	v_cndmask_b32_e32 v38, v21, v42, vcc
	v_cndmask_b32_e32 v41, v41, v22, vcc
	v_cndmask_b32_e32 v42, v42, v23, vcc
	v_lshlrev_b32_e32 v28, 16, v37
	v_and_b32_e32 v29, 0xffff0000, v37
	v_lshlrev_b32_e32 v30, 16, v38
	v_and_b32_e32 v31, 0xffff0000, v38
	ds_write_b128 v36, v[28:31]
	v_lshlrev_b32_e32 v28, 16, v41
	v_and_b32_e32 v29, 0xffff0000, v41
	v_lshlrev_b32_e32 v30, 16, v42
	v_and_b32_e32 v31, 0xffff0000, v42
	ds_write_b128 v36, v[28:31] offset:32
.LBB0_815:
	s_andn2_saveexec_b64 s[44:45], s[44:45]
	s_cbranch_execz .LBB0_817
	v_add_u32_e32 v28, v28, v120
	s_waitcnt vmcnt(6)
	ds_write_b128 v28, v[20:23]
.LBB0_817:
	s_or_b64 exec, exec, s[44:45]
	s_cmpk_gt_u32 s54, 0x7d
	s_cbranch_scc1 .Lld_skip5
	v_add_co_u32_e32 v20, vcc, 0x16c03000, v46
	s_nop 1
	v_addc_co_u32_e32 v21, vcc, 0, v47, vcc
	global_load_dwordx4 v[20:23], v[20:21], off
.Lld_skip5:
	v_add_u32_e32 v28, s4, v122
	s_and_saveexec_b64 s[0:1], s[22:23]
	s_xor_b64 s[44:45], exec, s[0:1]
	s_cbranch_execz .LBB0_819
	v_lshl_add_u32 v28, v123, 2, v28
	v_add3_u32 v36, v28, v133, s53
	s_waitcnt vmcnt(6)
	s_mov_b32 vcc_lo, 0xaaaaaaaa
	s_mov_b32 vcc_hi, 0xaaaaaaaa
	v_cndmask_b32_e32 v37, v26, v24, vcc
	v_cndmask_b32_e32 v38, v27, v25, vcc
	v_add_u32_e32 v40, -16, v36
	v_cndmask_b32_e32 v36, v36, v40, vcc
	v_mov_b32_dpp v41, v37 quad_perm:[1,0,3,2] row_mask:0xf bank_mask:0xf bound_ctrl:1
	v_mov_b32_dpp v42, v38 quad_perm:[1,0,3,2] row_mask:0xf bank_mask:0xf bound_ctrl:1
	v_cndmask_b32_e32 v37, v24, v41, vcc
	v_cndmask_b32_e32 v38, v25, v42, vcc
	v_cndmask_b32_e32 v41, v41, v26, vcc
	v_cndmask_b32_e32 v42, v42, v27, vcc
	v_lshlrev_b32_e32 v28, 16, v37
	v_and_b32_e32 v29, 0xffff0000, v37
	v_lshlrev_b32_e32 v30, 16, v38
	v_and_b32_e32 v31, 0xffff0000, v38
	ds_write_b128 v36, v[28:31]
	v_lshlrev_b32_e32 v28, 16, v41
	v_and_b32_e32 v29, 0xffff0000, v41
	v_lshlrev_b32_e32 v30, 16, v42
	v_and_b32_e32 v31, 0xffff0000, v42
	ds_write_b128 v36, v[28:31] offset:32
.LBB0_819:
	s_andn2_saveexec_b64 s[44:45], s[44:45]
	s_cbranch_execz .LBB0_821
	v_add_u32_e32 v28, v28, v124
	s_waitcnt vmcnt(6)
	ds_write_b128 v28, v[24:27]
.LBB0_821:
	s_or_b64 exec, exec, s[44:45]
	s_cmpk_gt_u32 s54, 0x7d
	s_cbranch_scc1 .Lld_skip6
	v_add_co_u32_e32 v24, vcc, 0x16c04000, v46
	s_nop 1
	v_addc_co_u32_e32 v25, vcc, 0, v47, vcc
	global_load_dwordx4 v[24:27], v[24:25], off
.Lld_skip6:
	s_cmpk_gt_u32 s54, 0x7d
	s_cbranch_scc0 .LBB0_824

.LBB0_824:
	s_cmp_eq_u32 s34, 0
	s_cbranch_scc1 .LBB0_786
